# SB half-block: ds_bpermute xor16/xor32 pulls replaced by v_permlane16/32_swap + cndmask (DPP-class cross-lane instead of LDS round trips)
# baseline (speedup 1.0000x reference)
; template <bool MASK>
; DI void sb_block(const LAS unsigned char* kb, const LAS unsigned char* vb, int koff, int s0, int tq, const bf16x8 (&qb)[4], f32x4 (&o)[8], float& R, int g, int r16) {
;     ...
;     for (int kt = 0; kt < 2; ++kt) { z[kt] = (f32x4){0.f, 0.f, 0.f, 0.f};
; #pragma unroll
;         for (int ks = 0; ks < 4; ++ks) { const bf16x8 a = *(const LAS bf16x8*)(kb + (koff + 16 * kt + r16) * 272 + (32 * ks + 8 * g) * 2); z[kt] = mfma16(a, qb[ks], z[kt]); } }
;     float suf[2][4], TT[2];
; #pragma unroll
;     for (int kt = 0; kt < 2; ++kt) {
;         float sp[4];
; #pragma unroll
;         for (int j = 0; j < 4; ++j) { const float zz = z[kt][j] * scl2; z[kt][j] = zz;
;             const float v = fmaxf(zz, 0.f) + __builtin_amdgcn_logf(1.f + __builtin_amdgcn_exp2f(-fabsf(zz)));
;             sp[j] = (!MASK || (s0 + 16 * kt + 4 * g + j < tq)) ? v : 0.f; }
;         const float s3 = sp[3], s2 = sp[2] + s3, s1 = sp[1] + s2, s0_ = sp[0] + s1;
;         const float o16 = __shfl_xor(s0_, 16), a2 = s0_ + o16, b2 = __shfl_xor(a2, 32);
;         const float E = ((g & 1) == 0 ? o16 : 0.f) + (g < 2 ? b2 : 0.f);
;         TT[kt] = a2 + b2; suf[kt][0] = s0_ + E; suf[kt][1] = s1 + E; suf[kt][2] = s2 + E; suf[kt][3] = s3 + E;
;     }
;     float base = R; float aw[2][4];
; #pragma unroll
;     ...
; #pragma unroll
;         for (int j = 0; j < 4; ++j) { const float v = __builtin_amdgcn_exp2f(z[kt][j] - (base + suf[kt][j])); aw[kt][j] = (!MASK || (s0 + 16 * kt + 4 * g + j < tq)) ? v : 0.f; }
;         base += TT[kt]; }
;     R = base;
;     u32x4 t; t.x = pk2(aw[0][0], aw[0][1]); t.y = pk2(aw[0][2], aw[0][3]); t.z = pk2(aw[1][0], aw[1][1]); t.w = pk2(aw[1][2], aw[1][3]); const bf16x8 bop = __builtin_bit_cast(bf16x8, t);
; #pragma unroll
;     for (int vt = 0; vt < 8; ++vt) { const LAS unsigned char* ap = vb + (16 * vt + r16) * 400 + (koff + 4 * g) * 2;
;         const bf16x8 a = cat4(*(const LAS s16x4*)ap, *(const LAS s16x4*)(ap + 32)); o[vt] = mfma16(a, bop, o[vt]); }
; DI void sb_phase(const Params& P, LAS unsigned char* lds) {
;     ...
; #pragma unroll 1
;     ...
;             if (s0 < 0) break;
;             if (s0 >= twmax) continue;
;             if (__all(R > SB_RDONE)) break;
;             if (s0 + 32 > twmax - 15) sb_block<true>(lds, lds + SB_VOFF, 32 * hb, s0, tq, qb, o, R, g, r16);
;             else sb_block<false>(lds, lds + SB_VOFF, 32 * hb, s0, tq, qb, o, R, g, r16); }
.LBB0_55:
	s_add_i32 s1, s64, 0x60
	s_cmp_lt_i32 s1, 0
	v_mov_b32_e32 v114, 33
	s_cbranch_scc1 .LBB0_65
	v_cmp_lt_i32_e32 vcc, s1, v0
	v_mov_b32_e32 v114, 35
	s_and_saveexec_b64 s[34:35], vcc
	s_cbranch_execz .LBB0_64
	v_cmp_lt_f32_e32 vcc, s97, v183
	s_cmp_eq_u64 vcc, exec
	s_mov_b32 s0, 33
	s_cbranch_scc1 .LBB0_63
	ds_read_b128 v[138:141], v148
	ds_read_b128 v[142:145], v148 offset:64
	ds_read_b128 v[134:137], v148 offset:128
	ds_read_b128 v[114:117], v148 offset:192
	ds_read_b128 v[130:133], v148 offset:4352
	ds_read_b128 v[126:129], v148 offset:4416
	ds_read_b128 v[122:125], v148 offset:4480
	ds_read_b128 v[118:121], v148 offset:4544
	v_add_u32_e32 v150, s68, v198
	v_cmp_le_i32_e32 vcc, s1, v146
	v_add_u32_e32 v161, 0xc800, v150
	v_add_u32_e32 v160, 0xe000, v150
	v_add_u32_e32 v159, 0xf800, v150
	v_add_u32_e32 v157, 0x11840, v150
	v_add_u32_e32 v158, 0x11860, v150
	v_add_u32_e32 v155, 0x13140, v150
	v_add_u32_e32 v156, 0x13160, v150
	v_add_u32_e32 v153, 0x14a40, v150
	v_add_u32_e32 v154, 0x14a60, v150
	v_add_u32_e32 v151, 0x16340, v150
	v_add_u32_e32 v152, 0x16360, v150
	v_add_u32_e32 v149, 0x17c40, v150
	v_add_u32_e32 v150, 0x17c60, v150
	s_and_saveexec_b64 s[0:1], vcc
	s_xor_b64 s[0:1], exec, s[0:1]
	s_cbranch_execz .LBB0_60
	s_waitcnt lgkmcnt(0)
	v_mfma_f32_16x16x32_bf16 v[138:141], v[138:141], v[110:113], 0
	s_mov_b32 s8, 0x3e0293ee
	v_mfma_f32_16x16x32_bf16 v[138:141], v[142:145], v[106:109], v[138:141]
	v_and_b32_e32 v143, 64, v231
	v_xor_b32_e32 v142, 16, v231
	v_add_u32_e32 v143, 64, v143
	v_mfma_f32_16x16x32_bf16 v[130:133], v[130:133], v[110:113], 0
	v_cmp_lt_i32_e32 vcc, v142, v143
	v_mfma_f32_16x16x32_bf16 v[134:137], v[134:137], v[102:105], v[138:141]
	v_mfma_f32_16x16x32_bf16 v[126:129], v[126:129], v[106:109], v[130:133]
	s_nop 1
	v_cndmask_b32_e32 v138, v231, v142, vcc
	v_lshlrev_b32_e32 v138, 2, v138
	v_xor_b32_e32 v139, 32, v231
	v_mfma_f32_16x16x32_bf16 v[114:117], v[114:117], v[98:101], v[134:137]
	v_cmp_lt_i32_e32 vcc, v139, v143
	v_mfma_f32_16x16x32_bf16 v[122:125], v[122:125], v[102:105], v[126:129]
	v_mfma_f32_16x16x32_bf16 v[118:121], v[118:121], v[98:101], v[122:125]
	ds_read2_b64 v[214:217], v161 offset0:168 offset1:172
	ds_read2_b64 v[218:221], v160 offset0:200 offset1:204
	ds_read2_b64 v[222:225], v159 offset0:232 offset1:236
	ds_read_b64 v[232:233], v157
	ds_read_b64 v[234:235], v158
	ds_read_b64 v[236:237], v155
	ds_read_b64 v[238:239], v156
	ds_read_b64 v[240:241], v153
	ds_read_b64 v[242:243], v154
	ds_read_b64 v[244:245], v151
	ds_read_b64 v[246:247], v152
	ds_read_b64 v[248:249], v149
	ds_read_b64 v[250:251], v150
	s_nop 4
	v_mul_f32_e32 v127, 0x3e0293ee, v117
	v_exp_f32_e64 v128, -|v127|
	v_mul_f32_e32 v135, 0x3e0293ee, v116
	v_exp_f32_e64 v141, -|v135|
	v_mul_f32_e32 v134, 0x3e0293ee, v115
	v_add_f32_e32 v123, 1.0, v128
	v_log_f32_e32 v124, v123
	v_mul_f32_e32 v123, 0x3e0293ee, v118
	v_exp_f32_e64 v125, -|v123|
	v_exp_f32_e64 v140, -|v134|
	v_max_f32_e32 v132, 0, v135
	v_add_f32_e32 v131, 1.0, v141
	v_max_f32_e32 v135, 0, v123
	v_mul_f32_e32 v123, 0x3e0293ee, v119
	v_add_f32_e32 v125, 1.0, v125
	v_log_f32_e32 v126, v131
	v_max_f32_e32 v122, 0, v127
	v_exp_f32_e64 v127, -|v123|
	v_log_f32_e32 v131, v125
	v_mul_f32_e32 v125, 0x3e0293ee, v120
	v_add_f32_e32 v140, 1.0, v140
	v_exp_f32_e64 v128, -|v125|
	v_mul_f32_e32 v129, 0x3e0293ee, v121
	v_log_f32_e32 v130, v140
	v_exp_f32_e64 v140, -|v129|
	v_max_f32_e32 v133, 0, v123
	v_add_f32_e32 v123, 1.0, v127
	v_log_f32_e32 v127, v123
	v_add_f32_e32 v123, 1.0, v128
	v_log_f32_e32 v123, v123
	v_add_f32_e32 v128, 1.0, v140
	v_log_f32_e32 v128, v128
	v_mul_f32_e32 v136, 0x3e0293ee, v114
	v_max_f32_e32 v125, 0, v125
	v_exp_f32_e64 v137, -|v136|
	v_add_f32_e32 v123, v125, v123
	v_max_f32_e32 v125, 0, v129
	v_add_f32_e32 v125, v125, v128
	v_max_f32_e32 v134, 0, v134
	v_pk_add_f32 v[126:127], v[132:133], v[126:127]
	v_pk_add_f32 v[122:123], v[122:123], v[124:125]
	v_pk_add_f32 v[128:129], v[134:135], v[130:131]
	v_pk_add_f32 v[126:127], v[126:127], v[122:123]
	v_add_f32_e32 v137, 1.0, v137
	v_pk_add_f32 v[128:129], v[128:129], v[126:127]
	v_log_f32_e32 v137, v137
	v_mov_b32_e32 v226, v129
	v_mov_b32_e32 v227, v129
	s_nop 1
	v_permlane16_swap_b32_e32 v226, v227
	v_cndmask_b32_e64 v131, v226, v227, s[36:37]
	v_max_f32_e32 v130, 0, v136
	v_cndmask_b32_e32 v124, v231, v139, vcc
	v_add_f32_e32 v130, v130, v137
	v_lshlrev_b32_e32 v124, 2, v124
	s_waitcnt lgkmcnt(0)
	v_pk_add_f32 v[132:133], v[128:129], v[130:131]
	v_mov_b32_e32 v226, v132
	v_mov_b32_e32 v227, v132
	s_nop 1
	v_permlane16_swap_b32_e32 v226, v227
	v_cndmask_b32_e64 v134, v226, v227, s[36:37]
	v_mov_b32_e32 v213, v133
	v_mov_b32_e32 v230, v133
	s_nop 1
	v_permlane32_swap_b32_e32 v213, v230
	v_cndmask_b32_e64 v135, v213, v230, s[38:39]
	s_waitcnt lgkmcnt(0)
	v_pk_add_f32 v[136:137], v[132:133], v[134:135]
	v_mov_b32_e32 v226, v136
	v_mov_b32_e32 v227, v136
	s_nop 1
	v_permlane32_swap_b32_e32 v226, v227
	v_cndmask_b32_e64 v182, v226, v227, s[38:39]
	v_cndmask_b32_e64 v124, 0, v134, s[36:37]
	s_waitcnt lgkmcnt(0)
	v_cndmask_b32_e64 v130, 0, v182, s[38:39]
	v_add_f32_e32 v124, v124, v130
	v_add_f32_e32 v130, v132, v124
	v_add_f32_e32 v128, v128, v124
	v_add_f32_e32 v132, v126, v124
	v_add_f32_e32 v122, v122, v124
	v_cndmask_b32_e64 v124, 0, v131, s[36:37]
	v_cndmask_b32_e64 v126, 0, v135, s[38:39]
	v_add_f32_e32 v124, v124, v126
	v_add_f32_e32 v126, v124, v129
	v_add_f32_e32 v127, v124, v127
	v_add_f32_e32 v123, v123, v124
	v_add_f32_e32 v124, v125, v124
	v_add_f32_e32 v125, v183, v126
	v_fma_f32 v118, v118, s8, -v125
	v_exp_f32_e32 v129, v118
	v_add_f32_e32 v118, v183, v127
	v_pk_add_f32 v[126:127], v[136:137], v[182:183]
	v_fma_f32 v118, v119, s8, -v118
	v_add_f32_e32 v119, v130, v127
	v_fma_f32 v114, v114, s8, -v119
	v_exp_f32_e32 v119, v114
	v_add_f32_e32 v114, v128, v127
	v_exp_f32_e32 v131, v118
	v_add_f32_e32 v118, v183, v123
	v_fma_f32 v114, v115, s8, -v114
	v_fma_f32 v118, v120, s8, -v118
	v_exp_f32_e32 v120, v114
	v_add_f32_e32 v114, v132, v127
	v_fma_f32 v114, v116, s8, -v114
	v_exp_f32_e32 v123, v114
	v_add_f32_e32 v114, v122, v127
	v_fma_f32 v122, v117, s8, -v114
	v_exp_f32_e32 v133, v118
	v_add_f32_e32 v118, v183, v124
	v_fma_f32 v118, v121, s8, -v118
	v_exp_f32_e32 v122, v122
	v_exp_f32_e32 v121, v118
	v_cvt_pk_bf16_f32 v118, v119, v120
	v_cvt_pk_bf16_f32 v120, v129, v131
	v_cvt_pk_bf16_f32 v119, v123, v122
	v_cvt_pk_bf16_f32 v121, v133, v121
	v_add_f32_e32 v183, v126, v127
	s_waitcnt lgkmcnt(0)
	s_nop 1
	v_mfma_f32_16x16x32_bf16 v[94:97], v[214:217], v[118:121], v[94:97]
	v_mfma_f32_16x16x32_bf16 v[90:93], v[218:221], v[118:121], v[90:93]
	v_mfma_f32_16x16x32_bf16 v[86:89], v[222:225], v[118:121], v[86:89]
	v_mfma_f32_16x16x32_bf16 v[82:85], v[232:235], v[118:121], v[82:85]
	v_mfma_f32_16x16x32_bf16 v[78:81], v[236:239], v[118:121], v[78:81]
	v_mfma_f32_16x16x32_bf16 v[70:73], v[244:247], v[118:121], v[70:73]
	v_mfma_f32_16x16x32_bf16 v[74:77], v[240:243], v[118:121], v[74:77]
	v_mfma_f32_16x16x32_bf16 v[34:37], v[248:251], v[118:121], v[34:37]
; #define LAS __attribute__((address_space(3)))
; DI f32x4 mfma16(bf16x8 a, bf16x8 b, f32x4 c) { return __builtin_amdgcn_mfma_f32_16x16x32_bf16(a, b, c, 0, 0, 0); }
; template <bool MASK>
; DI void sb_block(const LAS unsigned char* kb, const LAS unsigned char* vb, int koff, int s0, int tq, const bf16x8 (&qb)[4], f32x4 (&o)[8], float& R, int g, int r16) {
;     ...
;     for (int kt = 0; kt < 2; ++kt) { z[kt] = (f32x4){0.f, 0.f, 0.f, 0.f};
; #pragma unroll
;         for (int ks = 0; ks < 4; ++ks) { const bf16x8 a = *(const LAS bf16x8*)(kb + (koff + 16 * kt + r16) * 272 + (32 * ks + 8 * g) * 2); z[kt] = mfma16(a, qb[ks], z[kt]); } }
;     float suf[2][4], TT[2];
; #pragma unroll
;     for (int kt = 0; kt < 2; ++kt) {
;         float sp[4];
; #pragma unroll
;         for (int j = 0; j < 4; ++j) { const float zz = z[kt][j] * scl2; z[kt][j] = zz;
;             const float v = fmaxf(zz, 0.f) + __builtin_amdgcn_logf(1.f + __builtin_amdgcn_exp2f(-fabsf(zz)));
;             sp[j] = (!MASK || (s0 + 16 * kt + 4 * g + j < tq)) ? v : 0.f; }
;         const float s3 = sp[3], s2 = sp[2] + s3, s1 = sp[1] + s2, s0_ = sp[0] + s1;
;         const float o16 = __shfl_xor(s0_, 16), a2 = s0_ + o16, b2 = __shfl_xor(a2, 32);
;         const float E = ((g & 1) == 0 ? o16 : 0.f) + (g < 2 ? b2 : 0.f);
;         TT[kt] = a2 + b2; suf[kt][0] = s0_ + E; suf[kt][1] = s1 + E; suf[kt][2] = s2 + E; suf[kt][3] = s3 + E;
.LBB0_60:
	s_andn2_saveexec_b64 s[56:57], s[0:1]
	s_cbranch_execz .LBB0_62
	s_waitcnt lgkmcnt(0)
	v_mfma_f32_16x16x32_bf16 v[130:133], v[130:133], v[110:113], 0
	s_mov_b32 s8, 0x3e0293ee
	v_mfma_f32_16x16x32_bf16 v[138:141], v[138:141], v[110:113], 0
	v_mfma_f32_16x16x32_bf16 v[126:129], v[126:129], v[106:109], v[130:133]
	v_mfma_f32_16x16x32_bf16 v[138:141], v[142:145], v[106:109], v[138:141]
	v_mfma_f32_16x16x32_bf16 v[122:125], v[122:125], v[102:105], v[126:129]
	v_mfma_f32_16x16x32_bf16 v[134:137], v[134:137], v[102:105], v[138:141]
	v_mfma_f32_16x16x32_bf16 v[118:121], v[118:121], v[98:101], v[122:125]
	s_nop 5
	v_and_b32_e32 v124, 64, v231
	v_xor_b32_e32 v122, 16, v231
	v_add_u32_e32 v124, 64, v124
	v_cmp_lt_i32_e32 vcc, v122, v124
	v_mfma_f32_16x16x32_bf16 v[114:117], v[114:117], v[98:101], v[134:137]
	ds_read2_b64 v[214:217], v161 offset0:168 offset1:172
	ds_read2_b64 v[218:221], v160 offset0:200 offset1:204
	ds_read2_b64 v[222:225], v159 offset0:232 offset1:236
	ds_read_b64 v[232:233], v157
	ds_read_b64 v[234:235], v158
	ds_read_b64 v[236:237], v155
	ds_read_b64 v[238:239], v156
	ds_read_b64 v[240:241], v153
	ds_read_b64 v[242:243], v154
	ds_read_b64 v[244:245], v151
	ds_read_b64 v[246:247], v152
	ds_read_b64 v[248:249], v149
	ds_read_b64 v[250:251], v150
	v_mul_f32_e32 v133, 0x3e0293ee, v120
	v_cndmask_b32_e32 v122, v231, v122, vcc
	v_add_u32_e32 v123, s64, v178
	v_lshlrev_b32_e32 v135, 2, v122
	v_xor_b32_e32 v122, 32, v231
	v_cmp_lt_i32_e32 vcc, v122, v124
	s_nop 1
	v_mul_f32_e32 v125, 0x3e0293ee, v115
	v_max_f32_e32 v137, 0, v133
	v_cndmask_b32_e32 v122, v231, v122, vcc
	v_lshlrev_b32_e32 v136, 2, v122
	v_mul_f32_e32 v122, 0x3e0293ee, v114
	v_max_f32_e32 v124, 0, v122
	v_exp_f32_e64 v122, -|v122|
	v_exp_f32_e64 v133, -|v133|
	v_mul_f32_e32 v131, 0x3e0293ee, v119
	v_max_f32_e32 v129, 0, v131
	v_add_f32_e32 v122, 1.0, v122
	v_log_f32_e32 v122, v122
	v_add_f32_e32 v133, 1.0, v133
	v_log_f32_e32 v133, v133
	v_exp_f32_e64 v131, -|v131|
	v_add_f32_e32 v122, v124, v122
	v_max_f32_e32 v124, 0, v125
	v_exp_f32_e64 v125, -|v125|
	v_add_f32_e32 v133, v137, v133
	v_add_u32_e32 v137, 0x72, v123
	v_cmp_lt_i32_e64 s[44:45], v137, v184
	v_add_f32_e32 v125, 1.0, v125
	v_log_f32_e32 v126, v125
	v_mul_f32_e32 v125, 0x3e0293ee, v116
	v_max_f32_e32 v128, 0, v125
	v_exp_f32_e64 v125, -|v125|
	v_mul_f32_e32 v137, 0x3e0293ee, v121
	v_max_f32_e32 v138, 0, v137
	v_exp_f32_e64 v137, -|v137|
	v_add_f32_e32 v125, 1.0, v125
	v_log_f32_e32 v130, v125
	v_mul_f32_e32 v125, 0x3e0293ee, v117
	v_max_f32_e32 v127, 0, v125
	v_exp_f32_e64 v125, -|v125|
	v_add_f32_e32 v131, 1.0, v131
	v_add_f32_e32 v137, 1.0, v137
	v_log_f32_e32 v131, v131
	v_add_f32_e32 v125, 1.0, v125
	v_log_f32_e32 v125, v125
	v_log_f32_e32 v137, v137
	v_add_u32_e32 v134, 0x60, v123
	v_cndmask_b32_e64 v133, 0, v133, s[44:45]
	v_add_f32_e32 v125, v127, v125
	v_add_u32_e32 v127, 0x63, v123
	v_cmp_lt_i32_e64 s[0:1], v127, v184
	v_mul_f32_e32 v127, 0x3e0293ee, v118
	v_add_u32_e32 v123, 0x73, v123
	v_cndmask_b32_e64 v132, 0, v125, s[0:1]
	v_max_f32_e32 v125, 0, v127
	v_exp_f32_e64 v127, -|v127|
	v_cmp_lt_i32_e64 s[50:51], v123, v184
	v_or_b32_e32 v123, 16, v134
	v_add_f32_e32 v137, v138, v137
	v_add_f32_e32 v127, 1.0, v127
	v_log_f32_e32 v127, v127
	v_cmp_lt_i32_e64 s[52:53], v123, v147
	v_or_b32_e32 v123, 17, v134
	v_cndmask_b32_e64 v137, 0, v137, s[50:51]
	v_pk_add_f32 v[124:125], v[124:125], v[126:127]
	v_pk_add_f32 v[126:127], v[128:129], v[130:131]
	v_or_b32_e32 v128, 2, v134
	v_or_b32_e32 v138, 1, v134
	v_cmp_lt_i32_e64 s[48:49], v128, v184
	v_cmp_lt_i32_e64 s[54:55], v123, v147
	v_add_f32_e32 v133, v133, v137
	v_cmp_lt_i32_e64 s[46:47], v138, v184
	v_cndmask_b32_e64 v127, 0, v127, s[54:55]
	v_cndmask_b32_e64 v126, 0, v126, s[48:49]
	v_cndmask_b32_e64 v125, 0, v125, s[52:53]
	v_cndmask_b32_e64 v124, 0, v124, s[46:47]
	v_pk_add_f32 v[126:127], v[126:127], v[132:133]
	v_cmp_lt_i32_e32 vcc, v134, v184
	v_pk_add_f32 v[124:125], v[124:125], v[126:127]
	v_mov_b32_e32 v226, v125
	v_mov_b32_e32 v227, v125
	s_nop 1
	v_permlane16_swap_b32_e32 v226, v227
	v_cndmask_b32_e64 v123, v226, v227, s[36:37]
	v_cndmask_b32_e32 v122, 0, v122, vcc
	s_waitcnt lgkmcnt(0)
; #define LAS __attribute__((address_space(3)))
; DI unsigned pk2(float lo, float hi) { f32x2_t f = {lo, hi}; bf16x2_t v = __builtin_convertvector(f, bf16x2_t); return __builtin_bit_cast(unsigned, v); }
; DI f32x4 mfma16(bf16x8 a, bf16x8 b, f32x4 c) { return __builtin_amdgcn_mfma_f32_16x16x32_bf16(a, b, c, 0, 0, 0); }
; DI bf16x8 cat4(s16x4 lo, s16x4 hi) { return __builtin_shufflevector(lo, hi, 0, 1, 2, 3, 4, 5, 6, 7); }
; template <bool MASK>
; DI void sb_block(const LAS unsigned char* kb, const LAS unsigned char* vb, int koff, int s0, int tq, const bf16x8 (&qb)[4], f32x4 (&o)[8], float& R, int g, int r16) {
;     ...
;         const float s3 = sp[3], s2 = sp[2] + s3, s1 = sp[1] + s2, s0_ = sp[0] + s1;
;         const float o16 = __shfl_xor(s0_, 16), a2 = s0_ + o16, b2 = __shfl_xor(a2, 32);
;         const float E = ((g & 1) == 0 ? o16 : 0.f) + (g < 2 ? b2 : 0.f);
;         TT[kt] = a2 + b2; suf[kt][0] = s0_ + E; suf[kt][1] = s1 + E; suf[kt][2] = s2 + E; suf[kt][3] = s3 + E;
;     }
;     float base = R; float aw[2][4];
; #pragma unroll
;     ...
; #pragma unroll
;         for (int j = 0; j < 4; ++j) { const float v = __builtin_amdgcn_exp2f(z[kt][j] - (base + suf[kt][j])); aw[kt][j] = (!MASK || (s0 + 16 * kt + 4 * g + j < tq)) ? v : 0.f; }
;         base += TT[kt]; }
;     R = base;
;     u32x4 t; t.x = pk2(aw[0][0], aw[0][1]); t.y = pk2(aw[0][2], aw[0][3]); t.z = pk2(aw[1][0], aw[1][1]); t.w = pk2(aw[1][2], aw[1][3]); const bf16x8 bop = __builtin_bit_cast(bf16x8, t);
; #pragma unroll
;     for (int vt = 0; vt < 8; ++vt) { const LAS unsigned char* ap = vb + (16 * vt + r16) * 400 + (koff + 4 * g) * 2;
;         const bf16x8 a = cat4(*(const LAS s16x4*)ap, *(const LAS s16x4*)(ap + 32)); o[vt] = mfma16(a, bop, o[vt]); }
	v_pk_add_f32 v[128:129], v[122:123], v[124:125]
	v_mov_b32_e32 v226, v128
	v_mov_b32_e32 v227, v128
	s_nop 1
	v_permlane16_swap_b32_e32 v226, v227
	v_cndmask_b32_e64 v130, v226, v227, s[36:37]
	v_mov_b32_e32 v213, v129
	v_mov_b32_e32 v230, v129
	s_nop 1
	v_permlane32_swap_b32_e32 v213, v230
	v_cndmask_b32_e64 v131, v213, v230, s[38:39]
	v_cndmask_b32_e64 v123, 0, v123, s[36:37]
	s_waitcnt lgkmcnt(0)
	v_cndmask_b32_e64 v122, 0, v130, s[36:37]
	v_pk_add_f32 v[134:135], v[128:129], v[130:131]
	v_mov_b32_e32 v226, v134
	v_mov_b32_e32 v227, v134
	s_nop 1
	v_permlane32_swap_b32_e32 v226, v227
	v_cndmask_b32_e64 v182, v226, v227, s[38:39]
	s_waitcnt lgkmcnt(0)
	v_cndmask_b32_e64 v129, 0, v182, s[38:39]
	v_add_f32_e32 v122, v122, v129
	v_cndmask_b32_e64 v129, 0, v131, s[38:39]
	v_add_f32_e32 v123, v123, v129
	v_add_f32_e32 v125, v123, v125
	v_add_f32_e32 v125, v183, v125
	v_fma_f32 v118, v118, s8, -v125
	v_exp_f32_e32 v118, v118
	v_add_f32_e32 v127, v123, v127
	v_add_f32_e32 v129, v123, v133
	v_add_f32_e32 v123, v137, v123
	v_cndmask_b32_e64 v125, 0, v118, s[52:53]
	v_add_f32_e32 v118, v183, v127
	v_fma_f32 v118, v119, s8, -v118
	v_exp_f32_e32 v118, v118
	v_add_f32_e32 v128, v122, v128
	v_add_f32_e32 v124, v124, v122
	v_add_f32_e32 v126, v126, v122
	v_cndmask_b32_e64 v127, 0, v118, s[54:55]
	v_add_f32_e32 v118, v183, v129
	v_fma_f32 v118, v120, s8, -v118
	v_exp_f32_e32 v118, v118
	v_add_f32_e32 v122, v132, v122
	v_readlane_b32 s54, v254, 46
	v_readlane_b32 s55, v254, 47
	v_cndmask_b32_e64 v120, 0, v118, s[44:45]
	v_add_f32_e32 v118, v183, v123
	v_fma_f32 v118, v121, s8, -v118
	v_exp_f32_e32 v118, v118
	s_nop 0
	v_cndmask_b32_e64 v121, 0, v118, s[50:51]
	v_pk_add_f32 v[118:119], v[134:135], v[182:183]
	s_nop 0
	v_add_f32_e32 v123, v128, v119
	v_fma_f32 v114, v114, s8, -v123
	v_add_f32_e32 v123, v124, v119
	v_fma_f32 v115, v115, s8, -v123
	v_add_f32_e32 v123, v126, v119
	v_add_f32_e32 v122, v122, v119
	v_fma_f32 v116, v116, s8, -v123
	v_fma_f32 v117, v117, s8, -v122
	v_exp_f32_e32 v114, v114
	v_exp_f32_e32 v115, v115
	v_exp_f32_e32 v116, v116
	v_exp_f32_e32 v117, v117
	v_cndmask_b32_e32 v114, 0, v114, vcc
	v_cndmask_b32_e64 v115, 0, v115, s[46:47]
	v_cndmask_b32_e64 v116, 0, v116, s[48:49]
	v_cndmask_b32_e64 v117, 0, v117, s[0:1]
	v_add_f32_e32 v183, v118, v119
	v_cvt_pk_bf16_f32 v114, v114, v115
	v_cvt_pk_bf16_f32 v115, v116, v117
	v_cvt_pk_bf16_f32 v117, v120, v121
	v_cvt_pk_bf16_f32 v116, v125, v127
	s_waitcnt lgkmcnt(0)
	s_nop 1
	v_mfma_f32_16x16x32_bf16 v[94:97], v[214:217], v[114:117], v[94:97]
	v_mfma_f32_16x16x32_bf16 v[90:93], v[218:221], v[114:117], v[90:93]
	v_mfma_f32_16x16x32_bf16 v[86:89], v[222:225], v[114:117], v[86:89]
	v_mfma_f32_16x16x32_bf16 v[82:85], v[232:235], v[114:117], v[82:85]
	v_mfma_f32_16x16x32_bf16 v[78:81], v[236:239], v[114:117], v[78:81]
	v_mfma_f32_16x16x32_bf16 v[74:77], v[240:243], v[114:117], v[74:77]
	v_mfma_f32_16x16x32_bf16 v[70:73], v[244:247], v[114:117], v[70:73]
	v_mfma_f32_16x16x32_bf16 v[34:37], v[248:251], v[114:117], v[34:37]
